# w1 + attention epilogue norm-weight/lambda loads issued at key-loop exit + counted prologue Q wait
# baseline (speedup 1.0000x reference)
.Lpf_end:
	s_or_b64 exec, exec, s[94:95]
	s_cmp_lg_u64 s[28:29], 0
	s_waitcnt lgkmcnt(0)
	global_load_dwordx2 v[176:177], v1, s[18:19]
	global_load_dwordx4 v[160:163], v[110:111], off
	global_load_dwordx4 v[164:167], v[110:111], off offset:64
	global_load_dwordx4 v[168:171], v[110:111], off offset:128
	global_load_dwordx4 v[172:175], v[110:111], off offset:192
	global_load_dwordx4 v[204:207], v[110:111], off offset:256
	global_load_dwordx4 v[208:211], v[110:111], off offset:320
	global_load_dwordx4 v[212:215], v[110:111], off offset:384
	global_load_dwordx4 v[216:219], v[110:111], off offset:448
	v_mfma_f32_16x16x32_bf16 v[22:25], v[22:25], v[14:17], v[42:45]
	s_nop 2
	ds_read_b128 v[42:45], v0 offset:61440
	v_mfma_f32_16x16x32_bf16 v[26:29], v[26:29], v[14:17], v[34:37]
	s_nop 2
	ds_read_b128 v[34:37], v0 offset:59392
	s_waitcnt lgkmcnt(0)
	v_mfma_f32_16x16x32_bf16 v[42:45], v[42:45], v[14:17], v[46:49]
	s_nop 2
	ds_read_b128 v[46:49], v0 offset:63488
	s_waitcnt lgkmcnt(0)
	v_mfma_f32_16x16x32_bf16 v[46:49], v[46:49], v[14:17], v[38:41]
	s_nop 2
	ds_read_b128 v[38:41], v0 offset:50176
	v_mfma_f32_16x16x32_bf16 v[10:13], v[10:13], v[14:17], v[30:33]
	s_waitcnt lgkmcnt(0)
	v_mfma_f32_16x16x32_bf16 v[10:13], v[38:41], v[6:9], v[10:13]
	ds_read_b128 v[38:41], v0 offset:52224
	ds_read_b128 v[30:33], v0 offset:57344
	v_mfma_f32_16x16x32_bf16 v[18:21], v[18:21], v[14:17], v[50:53]
	s_waitcnt lgkmcnt(0)
	v_mfma_f32_16x16x32_bf16 v[18:21], v[38:41], v[6:9], v[18:21]
	ds_read_b128 v[38:41], v0 offset:54272
	s_waitcnt lgkmcnt(0)
	v_mfma_f32_16x16x32_bf16 v[22:25], v[38:41], v[6:9], v[22:25]
	ds_read_b128 v[38:41], v0 offset:56320
	s_waitcnt lgkmcnt(0)
	v_mfma_f32_16x16x32_bf16 v[26:29], v[38:41], v[6:9], v[26:29]
	ds_read_b128 v[38:41], v0 offset:58368
	v_mfma_f32_16x16x32_bf16 v[30:33], v[30:33], v[14:17], v[58:61]
	s_waitcnt lgkmcnt(0)
	v_mfma_f32_16x16x32_bf16 v[30:33], v[38:41], v[6:9], v[30:33]
	ds_read_b128 v[38:41], v0 offset:60416
	v_mfma_f32_16x16x32_bf16 v[34:37], v[34:37], v[14:17], v[54:57]
	s_waitcnt lgkmcnt(0)
	v_mfma_f32_16x16x32_bf16 v[34:37], v[38:41], v[6:9], v[34:37]
	ds_read_b128 v[38:41], v0 offset:62464
	s_waitcnt lgkmcnt(0)
	v_mfma_f32_16x16x32_bf16 v[38:41], v[38:41], v[6:9], v[42:45]
	s_nop 2
	ds_read_b128 v[42:45], v0 offset:64512
	s_waitcnt lgkmcnt(0)
	v_mfma_f32_16x16x32_bf16 v[42:45], v[42:45], v[6:9], v[46:49]
	s_nop 2
	v_mov_b64_e32 v[46:47], s[48:49]
	v_mov_b64_e32 v[48:49], s[50:51]
	s_nop 1
	v_mfma_f32_16x16x32_bf16 v[2:5], v[46:49], v[14:17], v[2:5]
	v_mfma_f32_16x16x32_bf16 v[2:5], v[46:49], v[6:9], v[2:5]
	s_cbranch_scc0 .LBB0_1337
	s_nop 6
	v_or_b32_e32 v4, s30, v129
	v_ashrrev_i32_e32 v5, 31, v4
	v_lshlrev_b64 v[4:5], 9, v[4:5]
	v_lshl_add_u64 v[4:5], s[28:29], 0, v[4:5]
	v_lshlrev_b32_e32 v0, 2, v106
	v_lshl_add_u64 v[4:5], v[4:5], 0, v[0:1]
	global_store_dwordx4 v[4:5], v[10:13], off
	global_store_dwordx4 v[4:5], v[18:21], off offset:64
	global_store_dwordx4 v[4:5], v[22:25], off offset:128
	global_store_dwordx4 v[4:5], v[26:29], off offset:192
	global_store_dwordx4 v[4:5], v[30:33], off offset:256
	global_store_dwordx4 v[4:5], v[34:37], off offset:320
	global_store_dwordx4 v[4:5], v[38:41], off offset:384
	global_store_dwordx4 v[4:5], v[42:45], off offset:448
	s_and_saveexec_b64 s[34:35], s[8:9]
	v_readlane_b32 s72, v255, 9
	v_readlane_b32 s73, v255, 10
	s_cbranch_execz .LBB0_1336
	s_add_i32 s0, s30, s70
	s_add_i32 s30, s0, 0x4000
	v_or_b32_e32 v4, s30, v109
	v_ashrrev_i32_e32 v5, 31, v4
	v_lshl_add_u64 v[4:5], v[4:5], 2, s[28:29]
	s_addk_i32 s0, 0x4080
	global_store_dword v[4:5], v113, off
	v_or_b32_e32 v4, s0, v109
	v_ashrrev_i32_e32 v5, 31, v4
	v_lshl_add_u64 v[4:5], v[4:5], 2, s[28:29]
	global_store_dword v[4:5], v2, off
